# v22 + post-attention LN: next-row loads issued at iteration top into fresh registers with counted vmcnt waits; radix-select prefix step: DPP scan + v_readlane broadcast instead of ds_bpermute chains
# speedup vs baseline: 1.0010x; 1.0010x over previous
; DI int bperm_i(int srclane, int v) { return __builtin_amdgcn_ds_bpermute(srclane << 2, v); }
; DI void dsa_index_phase(unsigned char* lds, KParamPtr P, int wv) {
;     ...
;         const unsigned long long mk = __ballot(found);
;         const int src = __ffsll((long long)mk) - 1;
;         d = bperm_i(src, d); Kr = bperm_i(src, nK);
;         prefix = (prefix << 8) | (unsigned)d;
.LBB0_875:
	s_or_b64 exec, exec, s[22:23]
	v_cndmask_b32_e64 v2, 0, 1, s[20:21]
	v_cmp_ne_u32_e64 s[18:19], 0, v2
	s_ff1_i32_b64 s2, s[18:19]
	s_cmp_lg_u64 s[18:19], 0
	s_cselect_b32 s2, s2, 63
	s_nop 3
	v_readlane_b32 s20, v5, s2
	v_readlane_b32 s21, v0, s2
	s_nop 0
	v_mov_b32_e32 v14, s21
	v_lshl_or_b32 v12, v12, 8, s20
